# left-over input-projection units moved beside the MLA up-projection phase (250-workgroup static order) + nt hints
# speedup vs baseline: 1.0198x; 1.0198x over previous
_ZN2fk3fwdENS_4ArgsE:
	s_mov_b32 s98, 0
	s_movk_i32 s99, 0x900
	s_movk_i32 s100, 0x8ff
	s_load_dwordx2 s[92:93], s[0:1], 0xc0
	s_load_dwordx4 s[88:91], s[0:1], 0xc8
	s_load_dword s3, s[0:1], 0xd8
	s_add_u32 s4, s0, 0xd8
	s_addc_u32 s5, s1, 0
	v_readfirstlane_b32 s68, v0
	v_writelane_b32 v254, s4, 0
	v_cmp_gt_u32_e64 s[6:7], 64, v0
	s_nop 0
	v_writelane_b32 v254, s5, 1
	s_mov_b64 s[4:5], exec
	v_writelane_b32 v254, s6, 2
	s_nop 1
	v_writelane_b32 v254, s7, 3
	s_and_b64 s[6:7], s[4:5], s[6:7]
	s_mov_b64 exec, s[6:7]
	v_lshl_add_u32 v1, v0, 2, 0
	v_add_u32_e32 v1, 0x27000, v1
	v_mov_b32_e32 v2, 0
	ds_write_b32 v1, v2
	s_or_b64 exec, exec, s[4:5]
	s_waitcnt lgkmcnt(0)
	s_add_u32 s94, s92, 0x4000
	s_addc_u32 s95, s93, 0
	s_sub_i32 s4, s89, s88
	s_mov_b32 s91, 0
	s_cmp_lt_i32 s4, 2
	v_cmp_eq_u32_e32 vcc, 0, v0
	s_barrier
	s_cbranch_scc1 .LBB0_7
	s_getreg_b32 s4, hwreg(HW_REG_XCC_ID, 0, 4)
	s_and_b32 s91, s4, 15
	s_and_saveexec_b64 s[4:5], vcc
	s_cbranch_execz .LBB0_6
	s_mov_b64 s[6:7], exec
	v_mbcnt_lo_u32_b32 v1, s6, 0
	v_mbcnt_hi_u32_b32 v1, s7, v1
	v_cmp_eq_u32_e32 vcc, 0, v1
	s_and_b64 s[8:9], exec, vcc
	s_mov_b64 exec, s[8:9]
	s_cbranch_execz .LBB0_6
	s_lshl_b32 s8, s91, 8
	s_bcnt1_i32_b64 s6, s[6:7]
	v_mov_b32_e32 v1, s8
	v_mov_b32_e32 v2, s6
	global_atomic_add v1, v2, s[94:95] offset:1024

.LBB0_450:
	v_writelane_b32 v254, s4, 27
	v_writelane_b32 v254, s5, 28
	v_writelane_b32 v254, s8, 29
	v_writelane_b32 v254, s14, 30
	v_writelane_b32 v254, s16, 31
	v_writelane_b32 v254, s22, 32
	v_writelane_b32 v254, s23, 33
	v_writelane_b32 v254, s24, 34
	v_writelane_b32 v254, s25, 35
	v_writelane_b32 v254, s26, 36
	v_writelane_b32 v254, s27, 37
	v_writelane_b32 v254, s28, 38
	v_writelane_b32 v254, s30, 39
	v_writelane_b32 v254, s42, 40
	v_writelane_b32 v254, s52, 41
	v_writelane_b32 v254, s53, 42
	v_writelane_b32 v254, s54, 43
	v_writelane_b32 v254, s55, 44
	v_writelane_b32 v254, s68, 45
	v_writelane_b32 v254, s75, 46
	v_writelane_b32 v254, s76, 47
	v_writelane_b32 v254, s78, 48
	v_writelane_b32 v254, s94, 49
	v_writelane_b32 v254, s95, 50
	s_nop 1
	v_mov_b32_e32 v255, v254
	s_cmp_lt_i32 s88, 3
	s_cselect_b64 s[18:19], -1, 0
	s_and_b64 s[0:1], s[18:19], s[4:5]
	v_writelane_b32 v254, s68, 6
	s_andn2_b64 vcc, exec, s[0:1]
	v_writelane_b32 v254, s94, 7
	s_nop 1
	v_writelane_b32 v254, s95, 8
	s_cbranch_vccnz .LBB0_628
	s_cmp_lt_i32 s2, s99
	s_cselect_b64 s[4:5], -1, 0
	s_cmp_gt_i32 s2, s100
	v_readfirstlane_b32 s0, v0
	s_cbranch_scc1 .LBB0_457
	s_ashr_i32 s1, s2, 31
	s_lshr_b32 s1, s1, 29
	s_add_i32 s1, s2, s1
	s_and_b32 s6, s1, -8
	s_sub_i32 s8, s2, s6
	s_cmp_gt_i32 s8, 5
	s_cbranch_scc0 .LBB0_454
	s_mul_i32 s6, s8, 0x120
	s_or_b32 s9, s6, 6
	s_cbranch_execz .LBB0_455
	s_branch .LBB0_456

.LBB0_460:
	s_add_u32 s28, s92, 0x21600000
	s_addc_u32 s29, s93, 0
	s_add_u32 s4, s92, 0x27900000
	s_addc_u32 s5, s93, 0
	v_writelane_b32 v254, s4, 11
	v_bfe_u32 v15, v0, 4, 2
	v_and_b32_e32 v1, 15, v0
	v_writelane_b32 v254, s5, 12
	s_add_u32 s4, s92, 0x2ab00000
	s_addc_u32 s5, s93, 0
	v_writelane_b32 v254, s4, 13
	v_lshlrev_b32_e32 v16, 4, v15
	s_waitcnt vmcnt(0)
	v_lshlrev_b32_e32 v18, 2, v0
	v_writelane_b32 v254, s5, 14
	s_add_u32 s4, s92, 0x400000
	s_addc_u32 s5, s93, 0
	v_writelane_b32 v254, s4, 15
	v_lshl_or_b32 v17, v1, 6, v16
	v_and_b32_e32 v18, 32, v18
	v_writelane_b32 v254, s5, 16
	s_add_u32 s4, s92, 0x300000
	v_writelane_b32 v254, s4, 17
	s_addc_u32 s4, s93, 0
	s_add_u32 s42, s92, 0x200000
	s_addc_u32 s43, s93, 0
	v_writelane_b32 v254, s4, 19
	s_add_u32 s4, s92, 0x210000
	s_addc_u32 s5, s93, 0
	v_writelane_b32 v254, s4, 21
	s_mov_b64 s[48:49], 0x80
	s_and_b32 s10, s1, 3
	v_writelane_b32 v254, s5, 22
	s_lshl_b32 s4, s38, 13
	v_bitop3_b32 v17, v17, s4, v18 bitop3:0xde
	v_lshlrev_b32_e32 v19, 6, v0
	s_movk_i32 s4, 0x3c0
	s_add_i32 m0, s34, 0x18000
	v_lshl_add_u64 v[8:9], v[8:9], 0, s[48:49]
	s_lshl_b32 s12, s10, 5
	v_and_or_b32 v16, v19, s4, v16
	s_lshl_b32 s4, s10, 12
	s_waitcnt vmcnt(2)
	s_barrier
	global_load_lds_dwordx4 v[8:9], off
	v_lshl_add_u64 v[6:7], v[6:7], 0, s[48:49]
	s_add_i32 m0, s34, 0x1a000
	s_add_i32 s11, s34, 0x8000
	s_add_i32 s46, s34, 0xa000
	v_bitop3_b32 v163, s4, v16, v18 bitop3:0xf6
	global_load_lds_dwordx4 v[6:7], off
	v_lshl_add_u64 v[2:3], v[2:3], 0, s[48:49]
	s_mov_b32 m0, s11
	s_add_u32 s4, s84, 0x100080
	global_load_lds_dwordx4 v[2:3], off
	v_lshl_add_u64 v[2:3], v[4:5], 0, s[48:49]
	s_mov_b32 m0, s46
	s_addc_u32 s5, s85, 0
	global_load_lds_dwordx4 v[2:3], off
	s_add_i32 m0, s34, 0x1c000
	v_lshl_add_u64 v[2:3], s[4:5], 0, v[140:141]
	global_load_lds_dwordx4 v[2:3], off
	v_lshl_add_u64 v[2:3], s[4:5], 0, v[144:145]
	s_add_i32 m0, s34, 0x1e000
	s_cmpk_lt_u32 s0, 0x100
	global_load_lds_dwordx4 v[2:3], off
	s_cselect_b64 s[50:51], -1, 0
	s_cmp_lt_u32 s10, 2
	s_cselect_b64 s[4:5], -1, 0
	s_cmp_eq_u32 s10, 0
	v_lshrrev_b32_e32 v14, 4, v0
	s_cselect_b64 s[8:9], -1, 0
	v_writelane_b32 v254, s8, 23
	v_bitop3_b32 v2, s1, v14, 3 bitop3:0xa8
	v_cmp_eq_u32_e64 s[0:1], 0, v2
	v_writelane_b32 v254, s9, 24
	v_lshl_or_b32 v148, s38, 6, v1
	v_writelane_b32 v254, s0, 25
	v_lshlrev_b32_e32 v3, 4, v148
	s_add_i32 s31, 0, 0x25000
	v_writelane_b32 v254, s1, 26
	s_lshl_b32 s0, s10, 2
	s_add_i32 s1, s0, 0
	s_add_i32 s10, s1, 0x25100
	v_add_u32_e32 v181, s10, v3
	s_add_i32 s10, s1, 0x25200
	v_add_u32_e32 v182, s10, v3
	s_add_i32 s10, s1, 0x25300
	v_add_u32_e32 v183, s10, v3
	s_add_i32 s10, s1, 0x25800
	v_add_u32_e32 v184, s10, v3
	s_add_i32 s10, s1, 0x25900
	v_add_u32_e32 v185, s10, v3
	s_add_i32 s10, s1, 0x25a00
	s_add_i32 s1, s1, 0x25b00
	v_add_u32_e32 v179, s31, v3
	v_add_u32_e32 v186, s10, v3
	v_add_u32_e32 v187, s1, v3
	v_lshlrev_b32_e32 v3, 10, v0
	v_and_b32_e32 v3, 0x60000, v3
	v_lshlrev_b32_e32 v4, 13, v12
	v_lshlrev_b32_e32 v151, 3, v15
	v_or3_b32 v3, v10, v3, v4
	v_or_b32_e32 v150, s12, v151
	v_add_u32_e32 v152, v3, v11
	v_lshlrev_b32_e32 v3, 6, v13
	s_waitcnt vmcnt(6)
	v_lshrrev_b32_e32 v2, 1, v150
	v_and_b32_e32 v3, 0xe0000, v3
	v_add_u32_e32 v180, s0, v179
	s_add_i32 s56, s31, s0
	v_or3_b32 v3, v10, v3, v4
	s_add_i32 s57, 0, 0x10000
	s_add_i32 s0, 0, 0x14000
	v_lshlrev_b32_e32 v191, 2, v2
	v_mbcnt_lo_u32_b32 v2, -1, 0
	v_mov_b32_e32 v149, v147
	v_or_b32_e32 v174, 16, v1
	v_or_b32_e32 v175, 32, v1
	v_or_b32_e32 v176, 48, v1
	v_cmp_eq_u32_e64 s[8:9], 0, v15
	v_lshlrev_b32_e32 v177, 5, v148
	v_and_or_b32 v178, s12, 32, v151
	s_ashr_i32 s47, s3, 31
	s_ashr_i32 s30, s2, 31
	v_mov_b32_e32 v153, v147
	v_add_u32_e32 v154, v3, v11
	v_mov_b32_e32 v155, v147
	v_mov_b32_e32 v156, s99
	v_mov_b32_e32 v158, s100
	v_mov_b32_e32 v157, 0
	v_mov_b32_e32 v159, 0
	v_add_u32_e32 v188, s57, v163
	v_add_u32_e32 v189, s0, v163
	v_add_u32_e32 v190, 0, v17
	s_movk_i32 s1, 0xf000
	s_movk_i32 s22, 0x1800
	s_mov_b32 s58, 0xc0000
	s_mov_b64 s[70:71], 0xd8000
	s_mov_b32 s59, 0xd8000
	s_mov_b64 s[72:73], 0xf0000
	s_mov_b32 s60, 0xf0000
	s_mov_b64 s[74:75], 0x108000
	s_mov_b32 s61, 0x108000
	v_mov_b32_e32 v192, 0x358637bd
	s_mov_b32 s23, 0xf800000
	v_mov_b32_e32 v193, 0x260
	v_mbcnt_hi_u32_b32 v194, -1, v2
	s_mov_b32 s62, 0
	s_barrier
	s_branch .LBB0_463

.LBB0_628:
	s_cmp_eq_u32 s98, 1
	s_cbranch_scc0 .Le9_p2end_normal
	s_mov_b32 s98, 2
	s_waitcnt vmcnt(0) lgkmcnt(0)
	s_barrier
	v_readlane_b32 s10, v254, 51
	v_readlane_b32 s11, v254, 52
	v_readlane_b32 s16, v254, 53
	v_readlane_b32 s18, v254, 54
	v_readlane_b32 s19, v254, 55
	v_readlane_b32 s22, v254, 56
	v_readlane_b32 s23, v254, 57
	v_readlane_b32 s24, v254, 58
	v_readlane_b32 s25, v254, 59
	v_readlane_b32 s26, v254, 60
	v_readlane_b32 s27, v254, 61
	v_readlane_b32 s28, v254, 62
	v_readlane_b32 s30, v254, 63
	v_readlane_b32 s94, v254, 49
	v_readlane_b32 s95, v254, 50
	s_addk_i32 s2, 0xf700
	s_nop 4
	s_branch .LBB0_751

.LBB0_678:
	s_cmp_lt_i32 s88, 4
	s_cselect_b64 s[10:11], -1, 0
	s_and_b64 s[0:1], s[10:11], s[4:5]
	s_andn2_b64 vcc, exec, s[0:1]
	s_cbranch_vccnz .LBB0_751
	s_cmp_lt_u32 s2, 6
	s_cbranch_scc0 .Le9_p3_others
	v_mov_b32_e32 v254, v255
	s_nop 1
	v_writelane_b32 v254, s10, 51
	v_writelane_b32 v254, s11, 52
	v_writelane_b32 v254, s16, 53
	v_writelane_b32 v254, s18, 54
	v_writelane_b32 v254, s19, 55
	v_writelane_b32 v254, s22, 56
	v_writelane_b32 v254, s23, 57
	v_writelane_b32 v254, s24, 58
	v_writelane_b32 v254, s25, 59
	v_writelane_b32 v254, s26, 60
	v_writelane_b32 v254, s27, 61
	v_writelane_b32 v254, s28, 62
	v_writelane_b32 v254, s30, 63
	s_nop 1
	v_readlane_b32 s4, v254, 27
	v_readlane_b32 s5, v254, 28
	v_readlane_b32 s8, v254, 29
	v_readlane_b32 s14, v254, 30
	v_readlane_b32 s16, v254, 31
	v_readlane_b32 s22, v254, 32
	v_readlane_b32 s23, v254, 33
	v_readlane_b32 s24, v254, 34
	v_readlane_b32 s25, v254, 35
	v_readlane_b32 s26, v254, 36
	v_readlane_b32 s27, v254, 37
	v_readlane_b32 s28, v254, 38
	v_readlane_b32 s30, v254, 39
	v_readlane_b32 s42, v254, 40
	v_readlane_b32 s52, v254, 41
	v_readlane_b32 s53, v254, 42
	v_readlane_b32 s54, v254, 43
	v_readlane_b32 s55, v254, 44
	v_readlane_b32 s68, v254, 45
	v_readlane_b32 s75, v254, 46
	v_readlane_b32 s76, v254, 47
	v_readlane_b32 s78, v254, 48
	v_readlane_b32 s94, v254, 49
	v_readlane_b32 s95, v254, 50
	s_mov_b32 s98, 1
	s_movk_i32 s99, 0x906
	s_movk_i32 s100, 0x905
	s_addk_i32 s2, 0x900
	s_nop 4
	s_branch .LBB0_450
.Le9_p3_others:
	s_add_i32 s2, s2, -6
	s_movk_i32 s3, 0xfa
	s_add_i32 s101, s2, 0x7d
	s_cmp_lt_u32 s101, 0xfa
	s_cbranch_scc1 .Le9_p3_go
	s_sub_i32 s101, s101, 0xfa
.Le9_p3_go:
	s_cmpk_gt_i32 s2, 0x317
	s_cselect_b64 s[4:5], -1, 0
	v_readfirstlane_b32 s6, v0
	s_and_b64 vcc, exec, s[4:5]
	s_cbranch_vccnz .LBB0_681
	s_ashr_i32 s0, s2, 31
	s_lshr_b32 s0, s0, 29
	s_add_i32 s0, s2, s0
	s_ashr_i32 s1, s0, 3
	s_and_b32 s0, s0, -8
	s_sub_i32 s0, s2, s0
	s_cmp_lt_i32 s0, 0
	s_movk_i32 s7, 0x64
	s_cselect_b32 s7, s7, 0x63
	s_mul_i32 s0, s0, s7
	s_add_i32 s0, s0, s1
	s_mul_hi_i32 s1, s0, 0x2aaaaaab
	s_lshr_b32 s7, s1, 31
	s_ashr_i32 s1, s1, 4
	s_add_i32 s1, s1, s7
	s_lshl_b32 s7, s1, 3
	s_sub_i32 s8, 0x42, s7
	s_mulk_i32 s1, 0x60
	s_min_u32 s9, s8, 8
	s_sub_i32 s12, s0, s1
	s_sext_i32_i8 s0, s12
	s_waitcnt vmcnt(0)
	v_cvt_f32_ubyte0_e32 v2, s9
	v_cvt_f32_i32_e32 v1, s0
	v_rcp_iflag_f32_e32 v3, v2
	s_ashr_i32 s0, s0, 30
	s_or_b32 s8, s0, 1
	v_mul_f32_e32 v3, v1, v3
	v_trunc_f32_e32 v3, v3
	v_fma_f32 v1, -v3, v2, v1
	v_cvt_i32_f32_e32 v3, v3
	v_cmp_ge_f32_e64 s[0:1], |v1|, v2
	s_and_b64 s[0:1], s[0:1], exec
	s_cselect_b32 s0, s8, 0
	v_readfirstlane_b32 s1, v3
	s_add_i32 s0, s1, s0
	s_sext_i32_i8 s8, s0
	s_mul_i32 s0, s0, s9
	s_sub_i32 s0, s12, s0
	s_sext_i32_i8 s0, s0
	s_waitcnt lgkmcnt(0)
	s_add_i32 s42, s7, s0

.LBB0_734:
	s_add_u32 s0, s92, 0x27900800
	s_addc_u32 s1, s93, 0
	s_waitcnt lgkmcnt(0)
	s_add_u32 s48, s92, 0x7400000
	s_addc_u32 s49, s93, 0
	s_nop 0
	s_mov_b32 s50, s101
	s_and_b32 s7, s50, 7
	s_lshr_b32 s8, s50, 3
	s_mulk_i32 s7, 0x84
	s_add_i32 s8, s8, s7
	v_readfirstlane_b32 s4, v0
	s_lshr_b32 s7, s8, 4
	s_lshr_b32 s6, s4, 6
	s_and_b32 s7, s7, 0x78
	s_and_b32 s9, s8, 7
	s_bfe_u32 s65, s8, 0x40003
	s_lshr_b32 s5, s4, 8
	s_lshl_b32 s51, s6, 10
	s_or_b32 s38, s7, s9
	s_lshl_b32 s8, s65, 18
	s_add_u32 s42, s48, s8
	s_addc_u32 s43, s49, 0
	s_add_i32 s52, s51, 0
	v_lshl_or_b32 v134, v163, 10, v161
	s_add_i32 m0, s52, 0x10000
	v_lshl_or_b32 v136, v164, 10, v161
	global_load_lds_dwordx4 v134, s[42:43]
	s_add_i32 m0, s52, 0x12000
	s_add_u32 s8, s42, 0x20000
	global_load_lds_dwordx4 v136, s[42:43]
	s_addc_u32 s9, s43, 0
	s_add_i32 m0, s52, 0x14000
	s_mul_i32 s7, s38, 0xc0000
	global_load_lds_dwordx4 v134, s[8:9]
	s_add_i32 m0, s52, 0x16000
	s_add_u32 s46, s0, s7
	s_addc_u32 s47, s1, 0
	s_add_i32 s53, s52, 0x2000
	global_load_lds_dwordx4 v136, s[8:9]
	v_lshl_add_u64 v[4:5], s[46:47], 0, v[130:131]
	s_mov_b32 m0, s52
	s_add_u32 s8, s46, 0x60000
	global_load_lds_dwordx4 v[4:5], off
	v_lshl_add_u64 v[2:3], s[46:47], 0, v[132:133]
	s_mov_b32 m0, s53
	s_addc_u32 s9, s47, 0
	s_add_i32 s54, s52, 0x4000
	global_load_lds_dwordx4 v[2:3], off
	v_lshl_add_u64 v[6:7], s[8:9], 0, v[130:131]
	s_mov_b32 m0, s54
	s_add_i32 s55, s52, 0x6000
	global_load_lds_dwordx4 v[6:7], off
	v_lshl_add_u64 v[6:7], s[8:9], 0, v[132:133]
	s_mov_b32 m0, s55
	v_mov_b32_e32 v135, 0
	global_load_lds_dwordx4 v[6:7], off
	v_mov_b32_e32 v137, v135
	s_cmp_eq_u32 s5, 1
	s_mov_b32 s56, 0
	v_lshl_add_u64 v[6:7], s[42:43], 0, v[134:135]
	s_cselect_b64 s[8:9], -1, 0
	s_cmp_lg_u32 s5, 1
	v_lshl_add_u64 v[8:9], s[42:43], 0, v[136:137]
	s_cbranch_scc1 .LBB0_736
	s_barrier

.LBB0_751:
	s_cmp_eq_u32 s98, 2
	s_cbranch_scc1 .Le9_p3end_done
	s_cmp_eq_u32 s3, 0xfa
	s_cbranch_scc0 .Le9_p3end_done
	s_add_i32 s2, s2, 6
	s_movk_i32 s3, 0x100

	.amdhsa_kernel _ZN2fk3fwdENS_4ArgsE
		.amdhsa_group_segment_fixed_size 0
		.amdhsa_private_segment_fixed_size 0
		.amdhsa_kernarg_size 472
		.amdhsa_user_sgpr_count 2
		.amdhsa_user_sgpr_dispatch_ptr 0
		.amdhsa_user_sgpr_queue_ptr 0
		.amdhsa_user_sgpr_kernarg_segment_ptr 1
		.amdhsa_user_sgpr_dispatch_id 0
		.amdhsa_user_sgpr_kernarg_preload_length 0
		.amdhsa_user_sgpr_kernarg_preload_offset 0
		.amdhsa_user_sgpr_private_segment_size 0
		.amdhsa_uses_dynamic_stack 0
		.amdhsa_enable_private_segment 0
		.amdhsa_system_sgpr_workgroup_id_x 1
		.amdhsa_system_sgpr_workgroup_id_y 0
		.amdhsa_system_sgpr_workgroup_id_z 0
		.amdhsa_system_sgpr_workgroup_info 0
		.amdhsa_system_vgpr_workitem_id 0
		.amdhsa_next_free_vgpr 256
		.amdhsa_next_free_sgpr 102
		.amdhsa_accum_offset 256
		.amdhsa_reserve_vcc 1
		.amdhsa_float_round_mode_32 0
		.amdhsa_float_round_mode_16_64 0
		.amdhsa_float_denorm_mode_32 3
		.amdhsa_float_denorm_mode_16_64 3
		.amdhsa_dx10_clamp 1
		.amdhsa_ieee_mode 1
		.amdhsa_fp16_overflow 0
		.amdhsa_tg_split 0
		.amdhsa_exception_fp_ieee_invalid_op 0
		.amdhsa_exception_fp_denorm_src 0
		.amdhsa_exception_fp_ieee_div_zero 0
		.amdhsa_exception_fp_ieee_overflow 0
		.amdhsa_exception_fp_ieee_underflow 0
		.amdhsa_exception_fp_ieee_inexact 0
		.amdhsa_exception_int_div_zero 0
	.end_amdhsa_kernel

amdhsa.kernels:
  - .agpr_count:     0
    .args:
      - .offset:         0
        .size:           216
        .value_kind:     by_value
      - .offset:         216
        .size:           4
        .value_kind:     hidden_block_count_x
      - .offset:         220
        .size:           4
        .value_kind:     hidden_block_count_y
      - .offset:         224
        .size:           4
        .value_kind:     hidden_block_count_z
      - .offset:         228
        .size:           2
        .value_kind:     hidden_group_size_x
      - .offset:         230
        .size:           2
        .value_kind:     hidden_group_size_y
      - .offset:         232
        .size:           2
        .value_kind:     hidden_group_size_z
      - .offset:         234
        .size:           2
        .value_kind:     hidden_remainder_x
      - .offset:         236
        .size:           2
        .value_kind:     hidden_remainder_y
      - .offset:         238
        .size:           2
        .value_kind:     hidden_remainder_z
      - .offset:         256
        .size:           8
        .value_kind:     hidden_global_offset_x
      - .offset:         264
        .size:           8
        .value_kind:     hidden_global_offset_y
      - .offset:         272
        .size:           8
        .value_kind:     hidden_global_offset_z
      - .offset:         280
        .size:           2
        .value_kind:     hidden_grid_dims
      - .offset:         336
        .size:           4
        .value_kind:     hidden_dynamic_lds_size
    .group_segment_fixed_size: 0
    .kernarg_segment_align: 8
    .kernarg_segment_size: 472
    .language:       OpenCL C
    .language_version:
      - 2
      - 0
    .max_flat_workgroup_size: 512
    .name:           _ZN2fk3fwdENS_4ArgsE
    .private_segment_fixed_size: 0
    .sgpr_count:     108
    .sgpr_spill_count: 43
    .symbol:         _ZN2fk3fwdENS_4ArgsE.kd
    .uniform_work_group_size: 1
    .uses_dynamic_stack: false
    .vgpr_count:     256
    .vgpr_spill_count: 0
    .wavefront_size: 64
